# hybrid role map: 8 WKV-scan workgroups per XCD, remaining workgroups keep XCD-contiguous role order (attention branch triplets share an L2)
# speedup vs baseline: 1.0155x; 1.0048x over previous
_Z3fwd4Args:
	s_load_dword s96, s[0:1], 0x148
	s_add_u32 s4, s0, 0x148
	s_addc_u32 s5, s1, 0
	s_mov_b32 s56, s2
	v_writelane_b32 v250, s4, 0
	s_waitcnt lgkmcnt(0)
	s_and_b32 s3, s96, 7
	s_cmp_lg_u32 s3, 0
	v_writelane_b32 v250, s5, 1
	v_writelane_b32 v250, s2, 2
	s_cbranch_scc1 .LBB0_2
	v_readlane_b32 s5, v250, 2
	s_cmp_eq_u32 s96, 0x100
	s_cbranch_scc1 .Lvcu_hybrid
	s_ashr_i32 s3, s5, 31
	s_lshr_b32 s3, s3, 29
	s_add_i32 s3, s5, s3
	s_and_b32 s4, s3, -8
	s_ashr_i32 s2, s96, 3
	s_sub_i32 s4, s5, s4
	s_mul_i32 s2, s2, s4
	s_ashr_i32 s3, s3, 3
	s_add_i32 s56, s2, s3
	s_branch .LBB0_2
.Lvcu_hybrid:
	s_and_b32 s4, s5, 7
	s_lshr_b32 s3, s5, 3
	s_cmp_lt_u32 s3, 8
	s_cbranch_scc0 .Lvcu_ns
	s_lshl_b32 s56, s4, 3
	s_add_i32 s56, s56, s3
	s_branch .LBB0_2
.Lvcu_ns:
	s_mul_i32 s56, s4, 24
	s_add_i32 s56, s56, s3
	s_add_i32 s56, s56, 56
